# fused post-norm GEMM epilogue de-serialised: residual loads of the second row half issued 12 at once (counted vmcnt) instead of a 16-step load/wait/store ladder; the 4 partial-sum loads after each sta
# speedup vs baseline: 1.0109x; 1.0109x over previous
.LBB0_78:
	s_waitcnt vmcnt(0) lgkmcnt(0)
	s_barrier
	s_and_saveexec_b64 s[4:5], s[10:11]
	s_cbranch_execz .LBB0_80
	v_readlane_b32 s14, v255, 5
	v_readlane_b32 s15, v255, 6
	s_waitcnt lgkmcnt(0)
	s_nop 0
	v_lshl_add_u64 v[144:145], v[226:227], 4, s[14:15]
	global_load_dword v146, v[144:145], off sc1
	global_load_dword v147, v[144:145], off offset:4 sc1
	global_load_dword v148, v[144:145], off offset:8 sc1
	global_load_dword v149, v[144:145], off offset:12 sc1
	s_waitcnt vmcnt(0)
	v_add_f32_e32 v146, 0, v146
	v_add_f32_e32 v146, v146, v147
	v_add_f32_e32 v146, v146, v148
	v_add_f32_e32 v144, v146, v149
	v_fmamk_f32 v144, v144, 0x3a800000, v236
	v_cmp_gt_f32_e32 vcc, s3, v144
	v_mul_f32_e32 v145, 0x4b800000, v144
	s_nop 0
	v_cndmask_b32_e32 v144, v144, v145, vcc
	v_rsq_f32_e32 v144, v144
	s_nop 0
	v_mul_f32_e32 v145, 0x45800000, v144
	v_cndmask_b32_e32 v144, v144, v145, vcc
	v_lshl_add_u32 v145, v250, 2, 0
	ds_write_b32 v145, v144 offset:4096
.LBB0_80:
	s_or_b64 exec, exec, s[4:5]
	v_lshlrev_b64 v[232:233], 2, v[224:225]
	s_waitcnt lgkmcnt(0)
	s_barrier
	s_waitcnt lgkmcnt(0)
	v_lshl_add_u64 v[144:145], s[60:61], 0, v[232:233]
	global_load_dwordx4 v[156:159], v[144:145], off
	global_load_dwordx4 v[152:155], v[144:145], off offset:64
	global_load_dwordx4 v[148:151], v[144:145], off offset:512
	s_nop 0
	global_load_dwordx4 v[144:147], v[144:145], off offset:576
	v_lshl_add_u32 v210, v228, 2, 0
	v_add_u32_e32 v249, 0x1000, v210
	ds_read2_b32 v[210:211], v249 offset1:16
	v_add_u32_e32 v228, s17, v228
	v_ashrrev_i32_e32 v229, 31, v228
	v_readlane_b32 s16, v255, 11
	v_readlane_b32 s17, v255, 12
	s_waitcnt lgkmcnt(0)
	v_pk_mul_f32 v[96:97], v[96:97], v[210:211] op_sel_hi:[1,0]
	v_pk_mul_f32 v[98:99], v[98:99], v[210:211] op_sel_hi:[1,0]
	v_pk_mul_f32 v[108:109], v[108:109], v[210:211] op_sel_hi:[1,0]
	v_pk_mul_f32 v[110:111], v[110:111], v[210:211] op_sel_hi:[1,0]
	v_pk_mul_f32 v[104:105], v[104:105], v[210:211] op_sel_hi:[1,0]
	v_pk_mul_f32 v[106:107], v[106:107], v[210:211] op_sel_hi:[1,0]
	v_pk_mul_f32 v[100:101], v[100:101], v[210:211] op_sel_hi:[1,0]
	v_pk_mul_f32 v[102:103], v[102:103], v[210:211] op_sel_hi:[1,0]
	s_andn2_b64 vcc, exec, s[16:17]
	s_waitcnt vmcnt(0)
	v_pk_fma_f32 v[108:109], v[156:157], v[108:109], v[204:205]
	v_lshlrev_b64 v[204:205], 12, v[228:229]
	v_lshl_add_u64 v[204:205], s[30:31], 0, v[204:205]
	v_pk_fma_f32 v[98:99], v[146:147], v[98:99], v[194:195]
	v_pk_fma_f32 v[96:97], v[144:145], v[96:97], v[192:193]
	v_add_u32_e32 v192, 16, v228
	v_mov_b32_e32 v194, v211
	v_ashrrev_i32_e32 v193, 31, v192
	v_pk_mul_f32 v[124:125], v[124:125], v[194:195] op_sel_hi:[1,0]
	v_pk_mul_f32 v[126:127], v[126:127], v[194:195] op_sel_hi:[1,0]
	v_pk_fma_f32 v[124:125], v[156:157], v[124:125], v[188:189]
	v_lshlrev_b64 v[188:189], 12, v[192:193]
	v_lshl_add_u64 v[188:189], s[30:31], 0, v[188:189]
	v_pk_mul_f32 v[120:121], v[120:121], v[194:195] op_sel_hi:[1,0]
	v_pk_mul_f32 v[122:123], v[122:123], v[194:195] op_sel_hi:[1,0]
	v_pk_mul_f32 v[116:117], v[116:117], v[194:195] op_sel_hi:[1,0]
	v_pk_mul_f32 v[118:119], v[118:119], v[194:195] op_sel_hi:[1,0]
	v_pk_mul_f32 v[112:113], v[112:113], v[194:195] op_sel_hi:[1,0]
	v_pk_mul_f32 v[114:115], v[114:115], v[194:195] op_sel_hi:[1,0]
	v_pk_fma_f32 v[110:111], v[158:159], v[110:111], v[206:207]
	v_lshl_add_u64 v[204:205], v[204:205], 0, v[232:233]
	v_pk_fma_f32 v[106:107], v[154:155], v[106:107], v[202:203]
	v_pk_fma_f32 v[104:105], v[152:153], v[104:105], v[200:201]
	v_pk_fma_f32 v[102:103], v[150:151], v[102:103], v[198:199]
	v_pk_fma_f32 v[100:101], v[148:149], v[100:101], v[196:197]
	v_pk_fma_f32 v[126:127], v[158:159], v[126:127], v[190:191]
	v_lshl_add_u64 v[188:189], v[188:189], 0, v[232:233]
	v_pk_fma_f32 v[122:123], v[154:155], v[122:123], v[186:187]
	v_pk_fma_f32 v[120:121], v[152:153], v[120:121], v[184:185]
	v_pk_fma_f32 v[118:119], v[150:151], v[118:119], v[182:183]
	v_pk_fma_f32 v[116:117], v[148:149], v[116:117], v[180:181]
	v_pk_fma_f32 v[114:115], v[146:147], v[114:115], v[178:179]
	v_pk_fma_f32 v[112:113], v[144:145], v[112:113], v[176:177]
	global_store_dwordx4 v[204:205], v[108:111], off
	global_store_dwordx4 v[204:205], v[104:107], off offset:64
	global_store_dwordx4 v[204:205], v[100:103], off offset:512
	global_store_dwordx4 v[204:205], v[96:99], off offset:576
	global_store_dwordx4 v[188:189], v[124:127], off
	global_store_dwordx4 v[188:189], v[120:123], off offset:64
	global_store_dwordx4 v[188:189], v[116:119], off offset:512
	global_store_dwordx4 v[188:189], v[112:115], off offset:576
	ds_read2_b32 v[178:179], v249 offset0:32 offset1:48
	v_add_u32_e32 v176, 32, v228
	v_ashrrev_i32_e32 v177, 31, v176
	s_waitcnt lgkmcnt(0)
	v_pk_mul_f32 v[80:81], v[80:81], v[178:179] op_sel_hi:[1,0]
	v_pk_mul_f32 v[82:83], v[82:83], v[178:179] op_sel_hi:[1,0]
	v_pk_fma_f32 v[80:81], v[144:145], v[80:81], v[160:161]
	v_pk_fma_f32 v[82:83], v[146:147], v[82:83], v[162:163]
	v_add_u32_e32 v160, 48, v228
	v_mov_b32_e32 v162, v179
	v_pk_mul_f32 v[92:93], v[92:93], v[178:179] op_sel_hi:[1,0]
	v_ashrrev_i32_e32 v161, 31, v160
	v_pk_mul_f32 v[76:77], v[76:77], v[162:163] op_sel_hi:[1,0]
	v_pk_mul_f32 v[64:65], v[64:65], v[162:163] op_sel_hi:[1,0]
	v_pk_fma_f32 v[92:93], v[156:157], v[92:93], v[172:173]
	v_lshlrev_b64 v[172:173], 12, v[176:177]
	v_pk_fma_f32 v[76:77], v[156:157], v[76:77], v[140:141]
	v_lshlrev_b64 v[140:141], 12, v[160:161]
	v_pk_fma_f32 v[64:65], v[144:145], v[64:65], v[128:129]
	v_add_u32_e32 v128, 0x80, v228
	v_pk_mul_f32 v[94:95], v[94:95], v[178:179] op_sel_hi:[1,0]
	v_lshl_add_u64 v[172:173], s[30:31], 0, v[172:173]
	v_pk_mul_f32 v[88:89], v[88:89], v[178:179] op_sel_hi:[1,0]
	v_pk_mul_f32 v[90:91], v[90:91], v[178:179] op_sel_hi:[1,0]
	v_pk_mul_f32 v[84:85], v[84:85], v[178:179] op_sel_hi:[1,0]
	v_pk_mul_f32 v[86:87], v[86:87], v[178:179] op_sel_hi:[1,0]
	v_pk_mul_f32 v[78:79], v[78:79], v[162:163] op_sel_hi:[1,0]
	v_lshl_add_u64 v[140:141], s[30:31], 0, v[140:141]
	v_pk_mul_f32 v[72:73], v[72:73], v[162:163] op_sel_hi:[1,0]
	v_pk_mul_f32 v[74:75], v[74:75], v[162:163] op_sel_hi:[1,0]
	v_pk_mul_f32 v[68:69], v[68:69], v[162:163] op_sel_hi:[1,0]
	v_pk_mul_f32 v[70:71], v[70:71], v[162:163] op_sel_hi:[1,0]
	v_pk_mul_f32 v[66:67], v[66:67], v[162:163] op_sel_hi:[1,0]
	v_ashrrev_i32_e32 v129, 31, v128
	v_pk_fma_f32 v[94:95], v[158:159], v[94:95], v[174:175]
	v_lshl_add_u64 v[172:173], v[172:173], 0, v[232:233]
	v_pk_fma_f32 v[90:91], v[154:155], v[90:91], v[170:171]
	v_pk_fma_f32 v[88:89], v[152:153], v[88:89], v[168:169]
	v_pk_fma_f32 v[86:87], v[150:151], v[86:87], v[166:167]
	v_pk_fma_f32 v[84:85], v[148:149], v[84:85], v[164:165]
	v_pk_fma_f32 v[78:79], v[158:159], v[78:79], v[142:143]
	v_lshl_add_u64 v[140:141], v[140:141], 0, v[232:233]
	v_pk_fma_f32 v[74:75], v[154:155], v[74:75], v[138:139]
	v_pk_fma_f32 v[72:73], v[152:153], v[72:73], v[136:137]
	v_pk_fma_f32 v[70:71], v[150:151], v[70:71], v[134:135]
	v_pk_fma_f32 v[68:69], v[148:149], v[68:69], v[132:133]
	v_pk_fma_f32 v[66:67], v[146:147], v[66:67], v[130:131]
	v_lshlrev_b64 v[130:131], 10, v[128:129]
	global_store_dwordx4 v[172:173], v[92:95], off
	global_store_dwordx4 v[172:173], v[88:91], off offset:64
	global_store_dwordx4 v[172:173], v[84:87], off offset:512
	global_store_dwordx4 v[172:173], v[80:83], off offset:576
	global_store_dwordx4 v[140:141], v[76:79], off
	global_store_dwordx4 v[140:141], v[72:75], off offset:64
	global_store_dwordx4 v[140:141], v[68:71], off offset:512
	global_store_dwordx4 v[140:141], v[64:67], off offset:576
	v_add_u32_e32 v130, 0x90, v228
	v_add_u32_e32 v132, 0xa0, v228
	v_add_u32_e32 v134, 0xb0, v228
	v_ashrrev_i32_e32 v131, 31, v130
	v_ashrrev_i32_e32 v133, 31, v132
	v_ashrrev_i32_e32 v135, 31, v134
	v_lshlrev_b64 v[162:163], 12, v[128:129]
	v_lshl_add_u64 v[162:163], v[230:231], 0, v[162:163]
	global_load_dwordx4 v[164:167], v[162:163], off
	global_load_dwordx4 v[168:171], v[162:163], off offset:64
	global_load_dwordx4 v[172:175], v[162:163], off offset:512
	global_load_dwordx4 v[180:183], v[162:163], off offset:576
	v_lshlrev_b64 v[162:163], 12, v[130:131]
	v_lshl_add_u64 v[162:163], v[230:231], 0, v[162:163]
	global_load_dwordx4 v[184:187], v[162:163], off
	global_load_dwordx4 v[188:191], v[162:163], off offset:64
	global_load_dwordx4 v[196:199], v[162:163], off offset:512
	global_load_dwordx4 v[200:203], v[162:163], off offset:576
	v_lshlrev_b64 v[162:163], 12, v[132:133]
	v_lshl_add_u64 v[162:163], v[230:231], 0, v[162:163]
	global_load_dwordx4 v[204:207], v[162:163], off
	global_load_dwordx4 v[136:139], v[162:163], off offset:64
	global_load_dwordx4 v[140:143], v[162:163], off offset:512
	global_load_dwordx4 v[210:213], v[162:163], off offset:576
	ds_read2_b32 v[194:195], v249 offset0:128 offset1:144
	ds_read2_b32 v[178:179], v249 offset0:160 offset1:176
	s_waitcnt lgkmcnt(0)
	v_pk_mul_f32 v[60:61], v[60:61], v[194:195] op_sel_hi:[1,0]
	v_pk_mul_f32 v[62:63], v[62:63], v[194:195] op_sel_hi:[1,0]
	v_pk_mul_f32 v[56:57], v[56:57], v[194:195] op_sel_hi:[1,0]
	v_pk_mul_f32 v[58:59], v[58:59], v[194:195] op_sel_hi:[1,0]
	v_pk_mul_f32 v[52:53], v[52:53], v[194:195] op_sel_hi:[1,0]
	v_pk_mul_f32 v[54:55], v[54:55], v[194:195] op_sel_hi:[1,0]
	v_pk_mul_f32 v[48:49], v[48:49], v[194:195] op_sel_hi:[1,0]
	v_pk_mul_f32 v[50:51], v[50:51], v[194:195] op_sel_hi:[1,0]
	v_mov_b32_e32 v194, v195
	v_pk_mul_f32 v[44:45], v[44:45], v[194:195] op_sel_hi:[1,0]
	v_pk_mul_f32 v[46:47], v[46:47], v[194:195] op_sel_hi:[1,0]
	v_pk_mul_f32 v[40:41], v[40:41], v[194:195] op_sel_hi:[1,0]
	v_pk_mul_f32 v[42:43], v[42:43], v[194:195] op_sel_hi:[1,0]
	v_pk_mul_f32 v[36:37], v[36:37], v[194:195] op_sel_hi:[1,0]
	v_pk_mul_f32 v[38:39], v[38:39], v[194:195] op_sel_hi:[1,0]
	v_pk_mul_f32 v[32:33], v[32:33], v[194:195] op_sel_hi:[1,0]
	v_pk_mul_f32 v[34:35], v[34:35], v[194:195] op_sel_hi:[1,0]
	v_pk_mul_f32 v[28:29], v[28:29], v[178:179] op_sel_hi:[1,0]
	v_pk_mul_f32 v[30:31], v[30:31], v[178:179] op_sel_hi:[1,0]
	v_pk_mul_f32 v[24:25], v[24:25], v[178:179] op_sel_hi:[1,0]
	v_pk_mul_f32 v[26:27], v[26:27], v[178:179] op_sel_hi:[1,0]
	v_pk_mul_f32 v[20:21], v[20:21], v[178:179] op_sel_hi:[1,0]
	v_pk_mul_f32 v[22:23], v[22:23], v[178:179] op_sel_hi:[1,0]
	v_pk_mul_f32 v[16:17], v[16:17], v[178:179] op_sel_hi:[1,0]
	v_pk_mul_f32 v[18:19], v[18:19], v[178:179] op_sel_hi:[1,0]
	v_mov_b32_e32 v178, v179
	v_pk_mul_f32 v[12:13], v[12:13], v[178:179] op_sel_hi:[1,0]
	v_pk_mul_f32 v[14:15], v[14:15], v[178:179] op_sel_hi:[1,0]
	v_pk_mul_f32 v[8:9], v[8:9], v[178:179] op_sel_hi:[1,0]
	v_pk_mul_f32 v[10:11], v[10:11], v[178:179] op_sel_hi:[1,0]
	v_pk_mul_f32 v[4:5], v[4:5], v[178:179] op_sel_hi:[1,0]
	v_pk_mul_f32 v[6:7], v[6:7], v[178:179] op_sel_hi:[1,0]
	v_pk_mul_f32 v[0:1], v[0:1], v[178:179] op_sel_hi:[1,0]
	v_pk_mul_f32 v[2:3], v[2:3], v[178:179] op_sel_hi:[1,0]
	v_lshlrev_b64 v[194:195], 10, v[128:129]
	v_lshl_add_u64 v[194:195], v[194:195], 0, v[224:225]
	v_lshl_add_u64 v[194:195], v[194:195], 2, s[30:31]
	s_waitcnt vmcnt(11)
	v_pk_fma_f32 v[60:61], v[156:157], v[60:61], v[164:165]
	v_pk_fma_f32 v[62:63], v[158:159], v[62:63], v[166:167]
	global_store_dwordx4 v[194:195], v[60:63], off
	s_waitcnt vmcnt(11)
	v_pk_fma_f32 v[56:57], v[152:153], v[56:57], v[168:169]
	v_pk_fma_f32 v[58:59], v[154:155], v[58:59], v[170:171]
	global_store_dwordx4 v[194:195], v[56:59], off offset:64
	s_waitcnt vmcnt(11)
	v_pk_fma_f32 v[52:53], v[148:149], v[52:53], v[172:173]
	v_pk_fma_f32 v[54:55], v[150:151], v[54:55], v[174:175]
	global_store_dwordx4 v[194:195], v[52:55], off offset:512
	s_waitcnt vmcnt(11)
	v_pk_fma_f32 v[48:49], v[144:145], v[48:49], v[180:181]
	v_pk_fma_f32 v[50:51], v[146:147], v[50:51], v[182:183]
	global_store_dwordx4 v[194:195], v[48:51], off offset:576
	v_lshlrev_b64 v[162:163], 12, v[134:135]
	v_lshl_add_u64 v[162:163], v[230:231], 0, v[162:163]
	global_load_dwordx4 v[164:167], v[162:163], off
	global_load_dwordx4 v[168:171], v[162:163], off offset:64
	global_load_dwordx4 v[172:175], v[162:163], off offset:512
	global_load_dwordx4 v[180:183], v[162:163], off offset:576
	v_lshlrev_b64 v[194:195], 10, v[130:131]
	v_lshl_add_u64 v[194:195], v[194:195], 0, v[224:225]
	v_lshl_add_u64 v[194:195], v[194:195], 2, s[30:31]
	s_waitcnt vmcnt(15)
	v_pk_fma_f32 v[44:45], v[156:157], v[44:45], v[184:185]
	v_pk_fma_f32 v[46:47], v[158:159], v[46:47], v[186:187]
	global_store_dwordx4 v[194:195], v[44:47], off
	s_waitcnt vmcnt(15)
	v_pk_fma_f32 v[40:41], v[152:153], v[40:41], v[188:189]
	v_pk_fma_f32 v[42:43], v[154:155], v[42:43], v[190:191]
	global_store_dwordx4 v[194:195], v[40:43], off offset:64
	s_waitcnt vmcnt(15)
	v_pk_fma_f32 v[36:37], v[148:149], v[36:37], v[196:197]
	v_pk_fma_f32 v[38:39], v[150:151], v[38:39], v[198:199]
	global_store_dwordx4 v[194:195], v[36:39], off offset:512
	s_waitcnt vmcnt(15)
	v_pk_fma_f32 v[32:33], v[144:145], v[32:33], v[200:201]
	v_pk_fma_f32 v[34:35], v[146:147], v[34:35], v[202:203]
	global_store_dwordx4 v[194:195], v[32:35], off offset:576
	v_lshlrev_b64 v[194:195], 10, v[132:133]
	v_lshl_add_u64 v[194:195], v[194:195], 0, v[224:225]
	v_lshl_add_u64 v[194:195], v[194:195], 2, s[30:31]
	s_waitcnt vmcnt(15)
	v_pk_fma_f32 v[28:29], v[156:157], v[28:29], v[204:205]
	v_pk_fma_f32 v[30:31], v[158:159], v[30:31], v[206:207]
	global_store_dwordx4 v[194:195], v[28:31], off
	s_waitcnt vmcnt(15)
	v_pk_fma_f32 v[24:25], v[152:153], v[24:25], v[136:137]
	v_pk_fma_f32 v[26:27], v[154:155], v[26:27], v[138:139]
	global_store_dwordx4 v[194:195], v[24:27], off offset:64
	s_waitcnt vmcnt(15)
	v_pk_fma_f32 v[20:21], v[148:149], v[20:21], v[140:141]
	v_pk_fma_f32 v[22:23], v[150:151], v[22:23], v[142:143]
	global_store_dwordx4 v[194:195], v[20:23], off offset:512
	s_waitcnt vmcnt(15)
	v_pk_fma_f32 v[16:17], v[144:145], v[16:17], v[210:211]
	v_pk_fma_f32 v[18:19], v[146:147], v[18:19], v[212:213]
	global_store_dwordx4 v[194:195], v[16:19], off offset:576
	v_lshlrev_b64 v[194:195], 10, v[134:135]
	v_lshl_add_u64 v[194:195], v[194:195], 0, v[224:225]
	v_lshl_add_u64 v[194:195], v[194:195], 2, s[30:31]
	s_waitcnt vmcnt(11)
	v_pk_fma_f32 v[12:13], v[156:157], v[12:13], v[164:165]
	v_pk_fma_f32 v[14:15], v[158:159], v[14:15], v[166:167]
	global_store_dwordx4 v[194:195], v[12:15], off
	s_waitcnt vmcnt(11)
	v_pk_fma_f32 v[8:9], v[152:153], v[8:9], v[168:169]
	v_pk_fma_f32 v[10:11], v[154:155], v[10:11], v[170:171]
	global_store_dwordx4 v[194:195], v[8:11], off offset:64
	s_waitcnt vmcnt(11)
	v_pk_fma_f32 v[4:5], v[148:149], v[4:5], v[172:173]
	v_pk_fma_f32 v[6:7], v[150:151], v[6:7], v[174:175]
	global_store_dwordx4 v[194:195], v[4:7], off offset:512
	s_waitcnt vmcnt(11)
	v_pk_fma_f32 v[0:1], v[144:145], v[0:1], v[180:181]
	v_pk_fma_f32 v[2:3], v[146:147], v[2:3], v[182:183]
	global_store_dwordx4 v[194:195], v[0:3], off offset:576
	s_cbranch_vccnz .LBB0_115
	v_mul_f32_e32 v136, v109, v109
	v_mul_f32_e32 v137, v111, v111
	v_fmac_f32_e32 v136, v108, v108
	v_fmac_f32_e32 v137, v110, v110
	v_add_f32_e32 v136, v136, v137
	v_mul_f32_e32 v137, v105, v105
	v_mul_f32_e32 v138, v107, v107
	v_fmac_f32_e32 v137, v104, v104
	v_fmac_f32_e32 v138, v106, v106
	v_add_f32_e32 v137, v137, v138
	v_add_f32_e32 v136, v136, v137
	v_mul_f32_e32 v137, v101, v101
	v_mul_f32_e32 v138, v103, v103
	v_fmac_f32_e32 v137, v100, v100
	v_fmac_f32_e32 v138, v102, v102
	v_add_f32_e32 v137, v137, v138
	v_add_f32_e32 v136, v137, v136
	v_mul_f32_e32 v137, v97, v97
	v_mul_f32_e32 v138, v99, v99
	v_fmac_f32_e32 v137, v96, v96
	v_fmac_f32_e32 v138, v98, v98
	v_add_f32_e32 v137, v137, v138
	v_add_f32_e32 v136, v137, v136
	ds_bpermute_b32 v137, v208, v136
	s_waitcnt lgkmcnt(0)
	v_add_f32_e32 v136, v136, v137
	ds_bpermute_b32 v137, v248, v136
	s_and_saveexec_b64 s[4:5], s[8:9]
	s_cbranch_execz .LBB0_83
	s_lshl_b32 s14, s66, 10
	s_add_i32 s14, s36, s14
	v_lshl_add_u32 v138, v221, 4, s14
	s_waitcnt lgkmcnt(0)
	v_add_f32_e32 v136, v136, v137
	ds_write_b32 v138, v136

.LBB0_112:
	s_waitcnt vmcnt(0) lgkmcnt(0)
	s_barrier
	s_and_saveexec_b64 s[4:5], s[10:11]
	s_cbranch_execz .LBB0_114
	s_waitcnt lgkmcnt(0)
	v_lshl_add_u64 v[136:137], v[226:227], 4, s[40:41]
	global_load_dword v138, v[136:137], off sc1
	global_load_dword v139, v[136:137], off offset:4 sc1
	global_load_dword v140, v[136:137], off offset:8 sc1
	global_load_dword v141, v[136:137], off offset:12 sc1
	s_waitcnt vmcnt(0)
	v_add_f32_e32 v138, 0, v138
	v_add_f32_e32 v138, v138, v139
	v_add_f32_e32 v138, v138, v140
	v_add_f32_e32 v136, v138, v141
	v_fmamk_f32 v136, v136, 0x3a800000, v236
	v_cmp_gt_f32_e32 vcc, s3, v136
	v_mul_f32_e32 v137, 0x4b800000, v136
	s_nop 0
	v_cndmask_b32_e32 v136, v136, v137, vcc
	v_rsq_f32_e32 v136, v136
	s_nop 0
	v_mul_f32_e32 v137, 0x45800000, v136
	v_cndmask_b32_e32 v136, v136, v137, vcc
	v_lshl_add_u32 v137, v250, 2, 0
	ds_write_b32 v137, v136 offset:4096

.LBB0_166:
	s_waitcnt vmcnt(0) lgkmcnt(0)
	s_barrier
	s_and_saveexec_b64 s[4:5], s[10:11]
	s_cbranch_execz .LBB0_168
	v_readlane_b32 s14, v255, 5
	v_readlane_b32 s15, v255, 6
	s_waitcnt lgkmcnt(0)
	s_nop 0
	v_lshl_add_u64 v[144:145], v[226:227], 4, s[14:15]
	global_load_dword v146, v[144:145], off sc1
	global_load_dword v147, v[144:145], off offset:4 sc1
	global_load_dword v148, v[144:145], off offset:8 sc1
	global_load_dword v149, v[144:145], off offset:12 sc1
	s_waitcnt vmcnt(0)
	v_add_f32_e32 v146, 0, v146
	v_add_f32_e32 v146, v146, v147
	v_add_f32_e32 v146, v146, v148
	v_add_f32_e32 v144, v146, v149
	v_fmamk_f32 v144, v144, 0x3a800000, v236
	v_cmp_gt_f32_e32 vcc, s3, v144
	v_mul_f32_e32 v145, 0x4b800000, v144
	s_nop 0
	v_cndmask_b32_e32 v144, v144, v145, vcc
	v_rsq_f32_e32 v144, v144
	s_nop 0
	v_mul_f32_e32 v145, 0x45800000, v144
	v_cndmask_b32_e32 v144, v144, v145, vcc
	v_lshl_add_u32 v145, v248, 2, 0
	ds_write_b32 v145, v144 offset:4096
.LBB0_168:
	s_or_b64 exec, exec, s[4:5]
	v_lshlrev_b64 v[232:233], 2, v[224:225]
	s_waitcnt lgkmcnt(0)
	s_barrier
	s_waitcnt lgkmcnt(0)
	v_lshl_add_u64 v[144:145], s[60:61], 0, v[232:233]
	global_load_dwordx4 v[156:159], v[144:145], off
	global_load_dwordx4 v[152:155], v[144:145], off offset:64
	global_load_dwordx4 v[148:151], v[144:145], off offset:512
	s_nop 0
	global_load_dwordx4 v[144:147], v[144:145], off offset:576
	v_lshl_add_u32 v210, v228, 2, 0
	v_add_u32_e32 v247, 0x1000, v210
	ds_read2_b32 v[210:211], v247 offset1:16
	v_add_u32_e32 v228, s17, v228
	v_ashrrev_i32_e32 v229, 31, v228
	v_readlane_b32 s4, v255, 11
	v_readlane_b32 s5, v255, 12
	s_waitcnt lgkmcnt(0)
	v_pk_mul_f32 v[96:97], v[96:97], v[210:211] op_sel_hi:[1,0]
	v_pk_mul_f32 v[98:99], v[98:99], v[210:211] op_sel_hi:[1,0]
	v_pk_mul_f32 v[108:109], v[108:109], v[210:211] op_sel_hi:[1,0]
	v_pk_mul_f32 v[110:111], v[110:111], v[210:211] op_sel_hi:[1,0]
	v_pk_mul_f32 v[104:105], v[104:105], v[210:211] op_sel_hi:[1,0]
	v_pk_mul_f32 v[106:107], v[106:107], v[210:211] op_sel_hi:[1,0]
	v_pk_mul_f32 v[100:101], v[100:101], v[210:211] op_sel_hi:[1,0]
	v_pk_mul_f32 v[102:103], v[102:103], v[210:211] op_sel_hi:[1,0]
	s_andn2_b64 vcc, exec, s[4:5]
	s_waitcnt vmcnt(0)
	v_pk_fma_f32 v[108:109], v[156:157], v[108:109], v[204:205]
	v_lshlrev_b64 v[204:205], 12, v[228:229]
	v_lshl_add_u64 v[204:205], s[30:31], 0, v[204:205]
	v_pk_fma_f32 v[98:99], v[146:147], v[98:99], v[194:195]
	v_pk_fma_f32 v[96:97], v[144:145], v[96:97], v[192:193]
	v_add_u32_e32 v192, 16, v228
	v_mov_b32_e32 v194, v211
	v_ashrrev_i32_e32 v193, 31, v192
	v_pk_mul_f32 v[124:125], v[124:125], v[194:195] op_sel_hi:[1,0]
	v_pk_mul_f32 v[126:127], v[126:127], v[194:195] op_sel_hi:[1,0]
	v_pk_fma_f32 v[124:125], v[156:157], v[124:125], v[188:189]
	v_lshlrev_b64 v[188:189], 12, v[192:193]
	v_lshl_add_u64 v[188:189], s[30:31], 0, v[188:189]
	v_pk_mul_f32 v[120:121], v[120:121], v[194:195] op_sel_hi:[1,0]
	v_pk_mul_f32 v[122:123], v[122:123], v[194:195] op_sel_hi:[1,0]
	v_pk_mul_f32 v[116:117], v[116:117], v[194:195] op_sel_hi:[1,0]
	v_pk_mul_f32 v[118:119], v[118:119], v[194:195] op_sel_hi:[1,0]
	v_pk_mul_f32 v[112:113], v[112:113], v[194:195] op_sel_hi:[1,0]
	v_pk_mul_f32 v[114:115], v[114:115], v[194:195] op_sel_hi:[1,0]
	v_pk_fma_f32 v[110:111], v[158:159], v[110:111], v[206:207]
	v_lshl_add_u64 v[204:205], v[204:205], 0, v[232:233]
	v_pk_fma_f32 v[106:107], v[154:155], v[106:107], v[202:203]
	v_pk_fma_f32 v[104:105], v[152:153], v[104:105], v[200:201]
	v_pk_fma_f32 v[102:103], v[150:151], v[102:103], v[198:199]
	v_pk_fma_f32 v[100:101], v[148:149], v[100:101], v[196:197]
	v_pk_fma_f32 v[126:127], v[158:159], v[126:127], v[190:191]
	v_lshl_add_u64 v[188:189], v[188:189], 0, v[232:233]
	v_pk_fma_f32 v[122:123], v[154:155], v[122:123], v[186:187]
	v_pk_fma_f32 v[120:121], v[152:153], v[120:121], v[184:185]
	v_pk_fma_f32 v[118:119], v[150:151], v[118:119], v[182:183]
	v_pk_fma_f32 v[116:117], v[148:149], v[116:117], v[180:181]
	v_pk_fma_f32 v[114:115], v[146:147], v[114:115], v[178:179]
	v_pk_fma_f32 v[112:113], v[144:145], v[112:113], v[176:177]
	global_store_dwordx4 v[204:205], v[108:111], off
	global_store_dwordx4 v[204:205], v[104:107], off offset:64
	global_store_dwordx4 v[204:205], v[100:103], off offset:512
	global_store_dwordx4 v[204:205], v[96:99], off offset:576
	global_store_dwordx4 v[188:189], v[124:127], off
	global_store_dwordx4 v[188:189], v[120:123], off offset:64
	global_store_dwordx4 v[188:189], v[116:119], off offset:512
	global_store_dwordx4 v[188:189], v[112:115], off offset:576
	ds_read2_b32 v[178:179], v247 offset0:32 offset1:48
	v_add_u32_e32 v176, 32, v228
	v_ashrrev_i32_e32 v177, 31, v176
	s_waitcnt lgkmcnt(0)
	v_pk_mul_f32 v[80:81], v[80:81], v[178:179] op_sel_hi:[1,0]
	v_pk_mul_f32 v[82:83], v[82:83], v[178:179] op_sel_hi:[1,0]
	v_pk_fma_f32 v[80:81], v[144:145], v[80:81], v[160:161]
	v_pk_fma_f32 v[82:83], v[146:147], v[82:83], v[162:163]
	v_add_u32_e32 v160, 48, v228
	v_mov_b32_e32 v162, v179
	v_pk_mul_f32 v[92:93], v[92:93], v[178:179] op_sel_hi:[1,0]
	v_ashrrev_i32_e32 v161, 31, v160
	v_pk_mul_f32 v[76:77], v[76:77], v[162:163] op_sel_hi:[1,0]
	v_pk_mul_f32 v[64:65], v[64:65], v[162:163] op_sel_hi:[1,0]
	v_pk_fma_f32 v[92:93], v[156:157], v[92:93], v[172:173]
	v_lshlrev_b64 v[172:173], 12, v[176:177]
	v_pk_fma_f32 v[76:77], v[156:157], v[76:77], v[140:141]
	v_lshlrev_b64 v[140:141], 12, v[160:161]
	v_pk_fma_f32 v[64:65], v[144:145], v[64:65], v[128:129]
	v_add_u32_e32 v128, 0x80, v228
	v_pk_mul_f32 v[94:95], v[94:95], v[178:179] op_sel_hi:[1,0]
	v_lshl_add_u64 v[172:173], s[30:31], 0, v[172:173]
	v_pk_mul_f32 v[88:89], v[88:89], v[178:179] op_sel_hi:[1,0]
	v_pk_mul_f32 v[90:91], v[90:91], v[178:179] op_sel_hi:[1,0]
	v_pk_mul_f32 v[84:85], v[84:85], v[178:179] op_sel_hi:[1,0]
	v_pk_mul_f32 v[86:87], v[86:87], v[178:179] op_sel_hi:[1,0]
	v_pk_mul_f32 v[78:79], v[78:79], v[162:163] op_sel_hi:[1,0]
	v_lshl_add_u64 v[140:141], s[30:31], 0, v[140:141]
	v_pk_mul_f32 v[72:73], v[72:73], v[162:163] op_sel_hi:[1,0]
	v_pk_mul_f32 v[74:75], v[74:75], v[162:163] op_sel_hi:[1,0]
	v_pk_mul_f32 v[68:69], v[68:69], v[162:163] op_sel_hi:[1,0]
	v_pk_mul_f32 v[70:71], v[70:71], v[162:163] op_sel_hi:[1,0]
	v_pk_mul_f32 v[66:67], v[66:67], v[162:163] op_sel_hi:[1,0]
	v_ashrrev_i32_e32 v129, 31, v128
	v_pk_fma_f32 v[94:95], v[158:159], v[94:95], v[174:175]
	v_lshl_add_u64 v[172:173], v[172:173], 0, v[232:233]
	v_pk_fma_f32 v[90:91], v[154:155], v[90:91], v[170:171]
	v_pk_fma_f32 v[88:89], v[152:153], v[88:89], v[168:169]
	v_pk_fma_f32 v[86:87], v[150:151], v[86:87], v[166:167]
	v_pk_fma_f32 v[84:85], v[148:149], v[84:85], v[164:165]
	v_pk_fma_f32 v[78:79], v[158:159], v[78:79], v[142:143]
	v_lshl_add_u64 v[140:141], v[140:141], 0, v[232:233]
	v_pk_fma_f32 v[74:75], v[154:155], v[74:75], v[138:139]
	v_pk_fma_f32 v[72:73], v[152:153], v[72:73], v[136:137]
	v_pk_fma_f32 v[70:71], v[150:151], v[70:71], v[134:135]
	v_pk_fma_f32 v[68:69], v[148:149], v[68:69], v[132:133]
	v_pk_fma_f32 v[66:67], v[146:147], v[66:67], v[130:131]
	v_lshlrev_b64 v[130:131], 10, v[128:129]
	global_store_dwordx4 v[172:173], v[92:95], off
	global_store_dwordx4 v[172:173], v[88:91], off offset:64
	global_store_dwordx4 v[172:173], v[84:87], off offset:512
	global_store_dwordx4 v[172:173], v[80:83], off offset:576
	global_store_dwordx4 v[140:141], v[76:79], off
	global_store_dwordx4 v[140:141], v[72:75], off offset:64
	global_store_dwordx4 v[140:141], v[68:71], off offset:512
	global_store_dwordx4 v[140:141], v[64:67], off offset:576
	v_add_u32_e32 v130, 0x90, v228
	v_add_u32_e32 v132, 0xa0, v228
	v_add_u32_e32 v134, 0xb0, v228
	v_ashrrev_i32_e32 v131, 31, v130
	v_ashrrev_i32_e32 v133, 31, v132
	v_ashrrev_i32_e32 v135, 31, v134
	v_lshlrev_b64 v[162:163], 12, v[128:129]
	v_lshl_add_u64 v[162:163], v[230:231], 0, v[162:163]
	global_load_dwordx4 v[164:167], v[162:163], off
	global_load_dwordx4 v[168:171], v[162:163], off offset:64
	global_load_dwordx4 v[172:175], v[162:163], off offset:512
	global_load_dwordx4 v[180:183], v[162:163], off offset:576
	v_lshlrev_b64 v[162:163], 12, v[130:131]
	v_lshl_add_u64 v[162:163], v[230:231], 0, v[162:163]
	global_load_dwordx4 v[184:187], v[162:163], off
	global_load_dwordx4 v[188:191], v[162:163], off offset:64
	global_load_dwordx4 v[196:199], v[162:163], off offset:512
	global_load_dwordx4 v[200:203], v[162:163], off offset:576
	v_lshlrev_b64 v[162:163], 12, v[132:133]
	v_lshl_add_u64 v[162:163], v[230:231], 0, v[162:163]
	global_load_dwordx4 v[204:207], v[162:163], off
	global_load_dwordx4 v[136:139], v[162:163], off offset:64
	global_load_dwordx4 v[140:143], v[162:163], off offset:512
	global_load_dwordx4 v[210:213], v[162:163], off offset:576
	ds_read2_b32 v[194:195], v247 offset0:128 offset1:144
	ds_read2_b32 v[178:179], v247 offset0:160 offset1:176
	s_waitcnt lgkmcnt(0)
	v_pk_mul_f32 v[60:61], v[60:61], v[194:195] op_sel_hi:[1,0]
	v_pk_mul_f32 v[62:63], v[62:63], v[194:195] op_sel_hi:[1,0]
	v_pk_mul_f32 v[56:57], v[56:57], v[194:195] op_sel_hi:[1,0]
	v_pk_mul_f32 v[58:59], v[58:59], v[194:195] op_sel_hi:[1,0]
	v_pk_mul_f32 v[52:53], v[52:53], v[194:195] op_sel_hi:[1,0]
	v_pk_mul_f32 v[54:55], v[54:55], v[194:195] op_sel_hi:[1,0]
	v_pk_mul_f32 v[48:49], v[48:49], v[194:195] op_sel_hi:[1,0]
	v_pk_mul_f32 v[50:51], v[50:51], v[194:195] op_sel_hi:[1,0]
	v_mov_b32_e32 v194, v195
	v_pk_mul_f32 v[44:45], v[44:45], v[194:195] op_sel_hi:[1,0]
	v_pk_mul_f32 v[46:47], v[46:47], v[194:195] op_sel_hi:[1,0]
	v_pk_mul_f32 v[40:41], v[40:41], v[194:195] op_sel_hi:[1,0]
	v_pk_mul_f32 v[42:43], v[42:43], v[194:195] op_sel_hi:[1,0]
	v_pk_mul_f32 v[36:37], v[36:37], v[194:195] op_sel_hi:[1,0]
	v_pk_mul_f32 v[38:39], v[38:39], v[194:195] op_sel_hi:[1,0]
	v_pk_mul_f32 v[32:33], v[32:33], v[194:195] op_sel_hi:[1,0]
	v_pk_mul_f32 v[34:35], v[34:35], v[194:195] op_sel_hi:[1,0]
	v_pk_mul_f32 v[28:29], v[28:29], v[178:179] op_sel_hi:[1,0]
	v_pk_mul_f32 v[30:31], v[30:31], v[178:179] op_sel_hi:[1,0]
	v_pk_mul_f32 v[24:25], v[24:25], v[178:179] op_sel_hi:[1,0]
	v_pk_mul_f32 v[26:27], v[26:27], v[178:179] op_sel_hi:[1,0]
	v_pk_mul_f32 v[20:21], v[20:21], v[178:179] op_sel_hi:[1,0]
	v_pk_mul_f32 v[22:23], v[22:23], v[178:179] op_sel_hi:[1,0]
	v_pk_mul_f32 v[16:17], v[16:17], v[178:179] op_sel_hi:[1,0]
	v_pk_mul_f32 v[18:19], v[18:19], v[178:179] op_sel_hi:[1,0]
	v_mov_b32_e32 v178, v179
	v_pk_mul_f32 v[12:13], v[12:13], v[178:179] op_sel_hi:[1,0]
	v_pk_mul_f32 v[14:15], v[14:15], v[178:179] op_sel_hi:[1,0]
	v_pk_mul_f32 v[8:9], v[8:9], v[178:179] op_sel_hi:[1,0]
	v_pk_mul_f32 v[10:11], v[10:11], v[178:179] op_sel_hi:[1,0]
	v_pk_mul_f32 v[4:5], v[4:5], v[178:179] op_sel_hi:[1,0]
	v_pk_mul_f32 v[6:7], v[6:7], v[178:179] op_sel_hi:[1,0]
	v_pk_mul_f32 v[0:1], v[0:1], v[178:179] op_sel_hi:[1,0]
	v_pk_mul_f32 v[2:3], v[2:3], v[178:179] op_sel_hi:[1,0]
	v_lshlrev_b64 v[194:195], 10, v[128:129]
	v_lshl_add_u64 v[194:195], v[194:195], 0, v[224:225]
	v_lshl_add_u64 v[194:195], v[194:195], 2, s[30:31]
	s_waitcnt vmcnt(11)
	v_pk_fma_f32 v[60:61], v[156:157], v[60:61], v[164:165]
	v_pk_fma_f32 v[62:63], v[158:159], v[62:63], v[166:167]
	global_store_dwordx4 v[194:195], v[60:63], off
	s_waitcnt vmcnt(11)
	v_pk_fma_f32 v[56:57], v[152:153], v[56:57], v[168:169]
	v_pk_fma_f32 v[58:59], v[154:155], v[58:59], v[170:171]
	global_store_dwordx4 v[194:195], v[56:59], off offset:64
	s_waitcnt vmcnt(11)
	v_pk_fma_f32 v[52:53], v[148:149], v[52:53], v[172:173]
	v_pk_fma_f32 v[54:55], v[150:151], v[54:55], v[174:175]
	global_store_dwordx4 v[194:195], v[52:55], off offset:512
	s_waitcnt vmcnt(11)
	v_pk_fma_f32 v[48:49], v[144:145], v[48:49], v[180:181]
	v_pk_fma_f32 v[50:51], v[146:147], v[50:51], v[182:183]
	global_store_dwordx4 v[194:195], v[48:51], off offset:576
	v_lshlrev_b64 v[162:163], 12, v[134:135]
	v_lshl_add_u64 v[162:163], v[230:231], 0, v[162:163]
	global_load_dwordx4 v[164:167], v[162:163], off
	global_load_dwordx4 v[168:171], v[162:163], off offset:64
	global_load_dwordx4 v[172:175], v[162:163], off offset:512
	global_load_dwordx4 v[180:183], v[162:163], off offset:576
	v_lshlrev_b64 v[194:195], 10, v[130:131]
	v_lshl_add_u64 v[194:195], v[194:195], 0, v[224:225]
	v_lshl_add_u64 v[194:195], v[194:195], 2, s[30:31]
	s_waitcnt vmcnt(15)
	v_pk_fma_f32 v[44:45], v[156:157], v[44:45], v[184:185]
	v_pk_fma_f32 v[46:47], v[158:159], v[46:47], v[186:187]
	global_store_dwordx4 v[194:195], v[44:47], off
	s_waitcnt vmcnt(15)
	v_pk_fma_f32 v[40:41], v[152:153], v[40:41], v[188:189]
	v_pk_fma_f32 v[42:43], v[154:155], v[42:43], v[190:191]
	global_store_dwordx4 v[194:195], v[40:43], off offset:64
	s_waitcnt vmcnt(15)
	v_pk_fma_f32 v[36:37], v[148:149], v[36:37], v[196:197]
	v_pk_fma_f32 v[38:39], v[150:151], v[38:39], v[198:199]
	global_store_dwordx4 v[194:195], v[36:39], off offset:512
	s_waitcnt vmcnt(15)
	v_pk_fma_f32 v[32:33], v[144:145], v[32:33], v[200:201]
	v_pk_fma_f32 v[34:35], v[146:147], v[34:35], v[202:203]
	global_store_dwordx4 v[194:195], v[32:35], off offset:576
	v_lshlrev_b64 v[194:195], 10, v[132:133]
	v_lshl_add_u64 v[194:195], v[194:195], 0, v[224:225]
	v_lshl_add_u64 v[194:195], v[194:195], 2, s[30:31]
	s_waitcnt vmcnt(15)
	v_pk_fma_f32 v[28:29], v[156:157], v[28:29], v[204:205]
	v_pk_fma_f32 v[30:31], v[158:159], v[30:31], v[206:207]
	global_store_dwordx4 v[194:195], v[28:31], off
	s_waitcnt vmcnt(15)
	v_pk_fma_f32 v[24:25], v[152:153], v[24:25], v[136:137]
	v_pk_fma_f32 v[26:27], v[154:155], v[26:27], v[138:139]
	global_store_dwordx4 v[194:195], v[24:27], off offset:64
	s_waitcnt vmcnt(15)
	v_pk_fma_f32 v[20:21], v[148:149], v[20:21], v[140:141]
	v_pk_fma_f32 v[22:23], v[150:151], v[22:23], v[142:143]
	global_store_dwordx4 v[194:195], v[20:23], off offset:512
	s_waitcnt vmcnt(15)
	v_pk_fma_f32 v[16:17], v[144:145], v[16:17], v[210:211]
	v_pk_fma_f32 v[18:19], v[146:147], v[18:19], v[212:213]
	global_store_dwordx4 v[194:195], v[16:19], off offset:576
	v_lshlrev_b64 v[194:195], 10, v[134:135]
	v_lshl_add_u64 v[194:195], v[194:195], 0, v[224:225]
	v_lshl_add_u64 v[194:195], v[194:195], 2, s[30:31]
	s_waitcnt vmcnt(11)
	v_pk_fma_f32 v[12:13], v[156:157], v[12:13], v[164:165]
	v_pk_fma_f32 v[14:15], v[158:159], v[14:15], v[166:167]
	global_store_dwordx4 v[194:195], v[12:15], off
	s_waitcnt vmcnt(11)
	v_pk_fma_f32 v[8:9], v[152:153], v[8:9], v[168:169]
	v_pk_fma_f32 v[10:11], v[154:155], v[10:11], v[170:171]
	global_store_dwordx4 v[194:195], v[8:11], off offset:64
	s_waitcnt vmcnt(11)
	v_pk_fma_f32 v[4:5], v[148:149], v[4:5], v[172:173]
	v_pk_fma_f32 v[6:7], v[150:151], v[6:7], v[174:175]
	global_store_dwordx4 v[194:195], v[4:7], off offset:512
	s_waitcnt vmcnt(11)
	v_pk_fma_f32 v[0:1], v[144:145], v[0:1], v[180:181]
	v_pk_fma_f32 v[2:3], v[146:147], v[2:3], v[182:183]
	global_store_dwordx4 v[194:195], v[0:3], off offset:576
	s_cbranch_vccnz .LBB0_203
	v_mul_f32_e32 v136, v109, v109
	v_mul_f32_e32 v137, v111, v111
	v_fmac_f32_e32 v136, v108, v108
	v_fmac_f32_e32 v137, v110, v110
	v_add_f32_e32 v136, v136, v137
	v_mul_f32_e32 v137, v105, v105
	v_mul_f32_e32 v138, v107, v107
	v_fmac_f32_e32 v137, v104, v104
	v_fmac_f32_e32 v138, v106, v106
	v_add_f32_e32 v137, v137, v138
	v_add_f32_e32 v136, v136, v137
	v_mul_f32_e32 v137, v101, v101
	v_mul_f32_e32 v138, v103, v103
	v_fmac_f32_e32 v137, v100, v100
	v_fmac_f32_e32 v138, v102, v102
	v_add_f32_e32 v137, v137, v138
	v_add_f32_e32 v136, v137, v136
	v_mul_f32_e32 v137, v97, v97
	v_mul_f32_e32 v138, v99, v99
	v_fmac_f32_e32 v137, v96, v96
	v_fmac_f32_e32 v138, v98, v98
	v_add_f32_e32 v137, v137, v138
	v_add_f32_e32 v136, v137, v136
	ds_bpermute_b32 v137, v208, v136
	s_waitcnt lgkmcnt(0)
	v_add_f32_e32 v136, v136, v137
	ds_bpermute_b32 v137, v223, v136
	s_and_saveexec_b64 s[4:5], s[8:9]
	s_cbranch_execz .LBB0_171
	s_lshl_b32 s14, s66, 10
	s_add_i32 s14, s36, s14
	v_lshl_add_u32 v138, v221, 4, s14
	s_waitcnt lgkmcnt(0)
	v_add_f32_e32 v136, v136, v137
	ds_write_b32 v138, v136

.LBB0_200:
	s_waitcnt vmcnt(0) lgkmcnt(0)
	s_barrier
	s_and_saveexec_b64 s[4:5], s[10:11]
	s_cbranch_execz .LBB0_202
	s_waitcnt lgkmcnt(0)
	v_lshl_add_u64 v[136:137], v[226:227], 4, s[40:41]
	global_load_dword v138, v[136:137], off sc1
	global_load_dword v139, v[136:137], off offset:4 sc1
	global_load_dword v140, v[136:137], off offset:8 sc1
	global_load_dword v141, v[136:137], off offset:12 sc1
	s_waitcnt vmcnt(0)
	v_add_f32_e32 v138, 0, v138
	v_add_f32_e32 v138, v138, v139
	v_add_f32_e32 v138, v138, v140
	v_add_f32_e32 v136, v138, v141
	v_fmamk_f32 v136, v136, 0x3a800000, v236
	v_cmp_gt_f32_e32 vcc, s3, v136
	v_mul_f32_e32 v137, 0x4b800000, v136
	s_nop 0
	v_cndmask_b32_e32 v136, v136, v137, vcc
	v_rsq_f32_e32 v136, v136
	s_nop 0
	v_mul_f32_e32 v137, 0x45800000, v136
	v_cndmask_b32_e32 v136, v136, v137, vcc
	v_lshl_add_u32 v137, v248, 2, 0
	ds_write_b32 v137, v136 offset:4096
